# attention: first three P.V MFMAs of each step issued inside the previous step's pack tail, the other five spread over the row-max region (first right behind the barrier)
# speedup vs baseline: 1.0067x; 1.0063x over previous
.LBB0_999:
	v_mfma_f32_32x32x16_bf16 v[20:35], v[80:83], v[164:167], v[20:35]
	v_lshl_add_u64 v[84:85], s[48:49], 0, v[190:191]
	s_cselect_b32 s49, s49, s51
	s_cselect_b32 s48, s48, s50
	s_cselect_b32 s43, s38, s40
	global_load_lds_dwordx4 v[84:85], off
	v_lshl_add_u64 v[84:85], s[48:49], 0, v[192:193]
	s_add_i32 m0, s21, s43
	s_add_i32 s43, s23, s40
	global_load_lds_dwordx4 v[84:85], off
	v_lshl_add_u64 v[84:85], s[50:51], 0, v[194:195]
	s_add_i32 m0, s43, 0xd000
	s_mov_b32 s43, s39
	global_load_lds_dwordx4 v[84:85], off
	s_mov_b32 s39, s44
	s_mov_b32 s44, s15
	s_mov_b32 s45, s14
	v_max3_f32 v2, v52, v36, v53
	s_nop 0
	v_max3_f32 v2, v2, v37, v54
	s_nop 0
	v_mfma_f32_32x32x16_bf16 v[4:19], v[76:79], v[176:179], v[4:19]
	v_max3_f32 v2, v2, v38, v55
	s_nop 0
	v_max3_f32 v2, v2, v39, v56
	v_max3_f32 v68, v60, v44, v61
	v_max3_f32 v2, v2, v40, v57
	s_nop 0
	v_max3_f32 v68, v68, v45, v62
	v_mfma_f32_32x32x16_bf16 v[20:35], v[76:79], v[156:159], v[20:35]
	v_max3_f32 v2, v2, v41, v58
	s_nop 0
	v_max3_f32 v68, v68, v46, v63
	v_max3_f32 v68, v68, v47, v64
	v_max3_f32 v2, v2, v42, v59
	v_max3_f32 v68, v68, v48, v65
	s_nop 0
	v_mfma_f32_32x32x16_bf16 v[20:35], v[72:75], v[152:155], v[20:35]
	v_max3_f32 v68, v68, v49, v66
	v_max3_f32 v68, v68, v50, v67
	s_nop 0
	v_max3_f32 v2, v2, v43, v68
	s_nop 0
	v_max3_f32 v2, v2, v51, v2
	s_nop 0
	v_mfma_f32_32x32x16_bf16 v[4:19], v[72:75], v[148:151], v[4:19]
	v_mov_b32_e32 v68, v2
	v_mov_b32_e32 v69, v2
	s_nop 1
	v_permlane32_swap_b32_e32 v68, v69
	v_max3_f32 v2, v68, v69, v2
	s_nop 0
	v_cmp_lt_f32_e32 vcc, s56, v2
	s_cbranch_vccz .LBB0_1003
	v_add_f32_e32 v180, v210, v2
	v_cvt_pk_bf16_f32 v180, v180, v180
	v_lshlrev_b32_e32 v180, 16, v180
	v_cndmask_b32_e32 v180, v210, v180, vcc
	v_sub_f32_e32 v2, v210, v180
	v_sub_f32_e32 v84, v180, v210
	v_xor_b32_e32 v250, 0x80000000, v180
	v_min_f32_e32 v2, 0, v2
	v_lshrrev_b32_e32 v250, 16, v250
	v_exp_f32_e32 v2, v2
	v_cndmask_b32_e64 v250, 0, v250, s[2:3]
	s_and_saveexec_b64 s[14:15], s[2:3]
	ds_write_b32 v202, v2
	s_or_b64 exec, exec, s[14:15]
	ds_read_b32 v68, v1
	ds_read_b32 v69, v1 offset:4
	ds_read_b32 v70, v1 offset:8
	ds_read_b32 v71, v1 offset:12
	ds_read_b32 v72, v1 offset:32
	ds_read_b32 v73, v1 offset:36
	ds_read_b32 v74, v1 offset:40
	ds_read_b32 v75, v1 offset:44
	ds_read_b32 v76, v1 offset:64
	ds_read_b32 v77, v1 offset:68
	ds_read_b32 v78, v1 offset:72
	ds_read_b32 v79, v1 offset:76
	ds_read_b32 v80, v1 offset:96
	ds_read_b32 v81, v1 offset:100
	ds_read_b32 v82, v1 offset:104
	ds_read_b32 v83, v1 offset:108
	v_mul_f32_e32 v209, v209, v2
	s_waitcnt lgkmcnt(0)
	v_pk_mul_f32 v[20:21], v[20:21], v[68:69]
	v_pk_mul_f32 v[22:23], v[22:23], v[70:71]
	v_pk_mul_f32 v[24:25], v[24:25], v[72:73]
	v_pk_mul_f32 v[26:27], v[26:27], v[74:75]
	v_pk_mul_f32 v[28:29], v[28:29], v[76:77]
	v_pk_mul_f32 v[30:31], v[30:31], v[78:79]
	v_pk_mul_f32 v[32:33], v[32:33], v[80:81]
	v_pk_mul_f32 v[34:35], v[34:35], v[82:83]
	v_pk_mul_f32 v[4:5], v[4:5], v[68:69]
	v_pk_mul_f32 v[6:7], v[6:7], v[70:71]
	v_pk_mul_f32 v[8:9], v[8:9], v[72:73]
	v_pk_mul_f32 v[10:11], v[10:11], v[74:75]
	v_pk_mul_f32 v[12:13], v[12:13], v[76:77]
	v_pk_mul_f32 v[14:15], v[14:15], v[78:79]
	v_pk_mul_f32 v[16:17], v[16:17], v[80:81]
	v_pk_mul_f32 v[18:19], v[18:19], v[82:83]
	v_sub_f32_e32 v36, v36, v84
	v_sub_f32_e32 v37, v37, v84
	v_sub_f32_e32 v38, v38, v84
	v_sub_f32_e32 v39, v39, v84
	v_sub_f32_e32 v40, v40, v84
	v_sub_f32_e32 v41, v41, v84
	v_sub_f32_e32 v42, v42, v84
	v_sub_f32_e32 v43, v43, v84
	v_sub_f32_e32 v44, v44, v84
	v_sub_f32_e32 v45, v45, v84
	v_sub_f32_e32 v46, v46, v84
	v_sub_f32_e32 v47, v47, v84
	v_sub_f32_e32 v48, v48, v84
	v_sub_f32_e32 v49, v49, v84
	v_sub_f32_e32 v50, v50, v84
	v_sub_f32_e32 v51, v51, v84
	v_sub_f32_e32 v52, v52, v84
	v_sub_f32_e32 v53, v53, v84
	v_sub_f32_e32 v54, v54, v84
	v_sub_f32_e32 v55, v55, v84
	v_sub_f32_e32 v56, v56, v84
	v_sub_f32_e32 v57, v57, v84
	v_sub_f32_e32 v58, v58, v84
	v_sub_f32_e32 v59, v59, v84
	v_sub_f32_e32 v60, v60, v84
	v_sub_f32_e32 v61, v61, v84
	v_sub_f32_e32 v62, v62, v84
	v_sub_f32_e32 v63, v63, v84
	v_sub_f32_e32 v64, v64, v84
	v_sub_f32_e32 v65, v65, v84
	v_sub_f32_e32 v66, v66, v84
	v_sub_f32_e32 v67, v67, v84
	s_mov_b32 s56, 0x41000000
	s_branch .LBB0_1004

.LBB0_1004:
	v_mfma_f32_32x32x16_bf16 v[68:83], v[246:249], v[250:253], 0
	v_mfma_f32_32x32x16_bf16 v[68:83], v[136:139], v[100:103], v[68:83]
	v_add_u32_e32 v2, s45, v189
	ds_read_b128 v[184:187], v2 offset:96
	ds_read_b128 v[210:213], v2 offset:128
	ds_read_b128 v[214:217], v2 offset:6752
	ds_read_b128 v[218:221], v2 offset:160
	ds_read_b128 v[222:225], v2 offset:6784
	ds_read_b128 v[226:229], v2 offset:6816
	v_add_u32_e32 v2, s39, v200
	ds_read_b128 v[176:179], v2 offset:53248
	ds_read_b128 v[164:167], v2 offset:53280
	ds_read_b128 v[230:233], v2 offset:57856
	ds_read_b128 v[238:241], v2 offset:57888
	ds_read_b128 v[160:163], v2 offset:53312
	ds_read_b128 v[156:159], v2 offset:53344
	ds_read_b128 v[242:245], v2 offset:57920
	ds_read_b128 v[152:155], v2 offset:57952
	v_mfma_f32_32x32x16_bf16 v[84:99], v[246:249], v[250:253], 0
	v_mfma_f32_32x32x16_bf16 v[84:99], v[132:135], v[100:103], v[84:99]
	v_exp_f32_e32 v52, v52
	v_exp_f32_e32 v183, v36
	v_exp_f32_e32 v132, v53
	v_exp_f32_e32 v53, v54
	v_mfma_f32_32x32x16_bf16 v[68:83], v[144:147], v[104:107], v[68:83]
	v_exp_f32_e32 v54, v38
	v_exp_f32_e32 v36, v55
	v_exp_f32_e32 v55, v56
	v_exp_f32_e32 v56, v40
	v_mfma_f32_32x32x16_bf16 v[84:99], v[128:131], v[104:107], v[84:99]
	v_exp_f32_e32 v40, v39
	v_exp_f32_e32 v38, v57
	v_exp_f32_e32 v57, v58
	v_exp_f32_e32 v58, v41
	v_mfma_f32_32x32x16_bf16 v[68:83], v[140:143], v[108:111], v[68:83]
	v_add_u32_e32 v181, s44, v189
	ds_read_b128 v[144:147], v181
	ds_read_b128 v[172:175], v181 offset:32
	ds_read_b128 v[136:139], v181 offset:6656
	ds_read_b128 v[168:171], v181 offset:64
	ds_read_b128 v[148:151], v181 offset:6688
	ds_read_b128 v[140:143], v181 offset:6720
	v_exp_f32_e32 v2, v37
	v_mfma_f32_32x32x16_bf16 v[84:99], v[124:127], v[108:111], v[84:99]
	v_exp_f32_e32 v124, v59
	v_exp_f32_e32 v41, v60
	v_add_f32_e32 v133, v52, v183
	v_add_f32_e32 v37, v53, v54
	s_waitcnt lgkmcnt(14)
	v_mfma_f32_32x32x16_bf16 v[68:83], v[214:217], v[112:115], v[68:83]
	v_exp_f32_e32 v214, v42
	v_exp_f32_e32 v59, v44
	v_exp_f32_e32 v60, v43
	v_exp_f32_e32 v126, v61
	v_mfma_f32_32x32x16_bf16 v[84:99], v[184:187], v[112:115], v[84:99]
	v_exp_f32_e32 v61, v62
	v_exp_f32_e32 v62, v45
	v_exp_f32_e32 v128, v63
	v_exp_f32_e32 v63, v64
	v_mfma_f32_32x32x16_bf16 v[68:83], v[222:225], v[116:119], v[68:83]
	v_exp_f32_e32 v216, v48
	v_exp_f32_e32 v64, v47
	v_exp_f32_e32 v130, v65
	v_mfma_f32_32x32x16_bf16 v[84:99], v[210:213], v[116:119], v[84:99]
	v_exp_f32_e32 v65, v66
	v_exp_f32_e32 v215, v46
	v_exp_f32_e32 v185, v50
	v_mfma_f32_32x32x16_bf16 v[68:83], v[226:229], v[120:123], v[68:83]
	v_exp_f32_e32 v66, v49
	v_exp_f32_e32 v134, v67
	v_add_f32_e32 v39, v55, v56
	v_add_f32_e32 v125, v57, v214
	v_mfma_f32_32x32x16_bf16 v[84:99], v[218:221], v[120:123], v[84:99]
	v_add_f32_e32 v127, v41, v59
	v_add_f32_e32 v129, v61, v215
	v_add_f32_e32 v131, v63, v216
	v_add_f32_e32 v135, v65, v185
	v_exp_f32_e32 v184, v51
	v_cvt_pk_bf16_f32 v42, v52, v132
	v_cvt_pk_bf16_f32 v43, v53, v36
	v_cvt_pk_bf16_f32 v44, v55, v38
	v_cvt_pk_bf16_f32 v45, v57, v124
	v_cvt_pk_bf16_f32 v46, v41, v126
	v_cvt_pk_bf16_f32 v47, v61, v128
	s_waitcnt lgkmcnt(0)
	v_mfma_f32_32x32x16_bf16 v[4:19], v[42:45], v[230:233], v[4:19]
	v_cvt_pk_bf16_f32 v48, v63, v130
	v_cvt_pk_bf16_f32 v49, v65, v134
	v_cvt_pk_bf16_f32 v50, v183, v2
	v_cvt_pk_bf16_f32 v51, v54, v40
	v_mfma_f32_32x32x16_bf16 v[20:35], v[42:45], v[176:179], v[20:35]
	v_cvt_pk_bf16_f32 v52, v56, v58
	v_cvt_pk_bf16_f32 v53, v214, v60
	v_cvt_pk_bf16_f32 v54, v59, v62
	v_cvt_pk_bf16_f32 v55, v215, v64
	v_mfma_f32_32x32x16_bf16 v[4:19], v[46:49], v[238:241], v[4:19]
	v_cvt_pk_bf16_f32 v56, v216, v66
	v_cvt_pk_bf16_f32 v57, v185, v184
	s_add_i32 s14, s46, 5
	s_min_u32 s14, s14, s37
	s_add_i32 s15, s46, 3
	s_min_u32 s46, s15, s37
	s_mulk_i32 s14, 0x3000
	s_add_u32 s14, s10, s14
	s_addc_u32 s15, s11, 0
	s_lshl_b32 s46, s46, 13
	s_add_u32 s46, s12, s46
	s_addc_u32 s47, s13, 0
	s_add_i32 m0, s22, s45
	s_and_b64 s[48:49], s[4:5], exec
	s_waitcnt vmcnt(3) lgkmcnt(0)
	s_barrier
	v_mfma_f32_32x32x16_bf16 v[20:35], v[46:49], v[164:167], v[20:35]
	v_lshl_add_u64 v[186:187], s[14:15], 0, v[190:191]
	s_cselect_b32 s15, s15, s47
	s_cselect_b32 s14, s14, s46
	global_load_lds_dwordx4 v[186:187], off
	v_lshl_add_u64 v[186:187], s[14:15], 0, v[192:193]
	s_cselect_b32 s14, s45, s39
	s_add_i32 m0, s21, s14
	s_add_i32 s14, s23, s39
	global_load_lds_dwordx4 v[186:187], off
	v_lshl_add_u64 v[186:187], s[46:47], 0, v[194:195]
	s_add_i32 m0, s14, 0xd000
	s_nop 0
	global_load_lds_dwordx4 v[186:187], off
	v_max3_f32 v41, v84, v68, v85
	v_max3_f32 v59, v92, v76, v93
	v_add_f32_e32 v132, v132, v2
	v_max3_f32 v41, v41, v69, v86
	v_max3_f32 v59, v59, v77, v94
	s_nop 0
	v_max3_f32 v41, v41, v70, v87
	v_mfma_f32_32x32x16_bf16 v[4:19], v[50:53], v[242:245], v[4:19]
	v_max3_f32 v41, v41, v71, v88
	v_max3_f32 v59, v59, v78, v95
	v_max3_f32 v41, v41, v72, v89
	v_max3_f32 v59, v59, v79, v96
	s_nop 0
	v_max3_f32 v41, v41, v73, v90
	v_max3_f32 v183, v41, v74, v91
	v_add_f32_e32 v41, v132, v133
	v_max3_f32 v59, v59, v80, v97
	v_add_f32_e64 v36, v36, v40
	v_add_f32_e64 v37, v37, v41
	v_mfma_f32_32x32x16_bf16 v[20:35], v[50:53], v[160:163], v[20:35]
	v_max3_f32 v59, v59, v81, v98
	v_max3_f32 v186, v59, v82, v99
	v_add_f32_e32 v59, v36, v37
	v_add_f32_e32 v36, v38, v58
	v_add_f32_e32 v37, v39, v59
	v_add_f32_e32 v61, v36, v37
	v_add_f32_e32 v36, v124, v60
	v_add_f32_e32 v37, v125, v61
	v_add_f32_e32 v63, v36, v37
	v_add_f32_e32 v36, v126, v62
	v_add_f32_e32 v37, v127, v63
	v_mfma_f32_32x32x16_bf16 v[20:35], v[54:57], v[156:159], v[20:35]
	v_add_f32_e32 v65, v36, v37
	v_add_f32_e32 v36, v128, v64
	v_add_f32_e32 v37, v129, v65
	v_add_f32_e32 v67, v36, v37
	v_add_f32_e32 v36, v130, v66
	v_add_f32_e32 v37, v131, v67
	v_add_f32_e32 v185, v36, v37
	v_add_f32_e32 v36, v134, v184
	v_add_f32_e32 v37, v135, v185
	v_add_f32_e32 v2, v36, v37
	v_max3_f32 v36, v183, v75, v186
	v_mfma_f32_32x32x16_bf16 v[4:19], v[54:57], v[152:155], v[4:19]
	v_add_f32_e32 v2, v209, v2
	v_max3_f32 v36, v36, v83, v36
	s_nop 0
	v_mov_b32_e32 v37, v36
	v_mov_b32_e32 v38, v36
	s_nop 0
	v_permlane32_swap_b32_e32 v37, v38
	v_max3_f32 v36, v37, v38, v36
	s_nop 0
	v_cmp_lt_f32_e32 vcc, s56, v36
	s_cbranch_vccz .LBB0_1008
	s_nop 0
	v_add_f32_e32 v210, v180, v36
	v_cvt_pk_bf16_f32 v210, v210, v210
	v_lshlrev_b32_e32 v210, 16, v210
	v_cndmask_b32_e32 v210, v180, v210, vcc
	v_sub_f32_e32 v36, v180, v210
	v_sub_f32_e32 v186, v210, v180
	v_xor_b32_e32 v250, 0x80000000, v210
	v_min_f32_e32 v36, 0, v36
	v_lshrrev_b32_e32 v250, 16, v250
	v_exp_f32_e32 v36, v36
	v_cndmask_b32_e64 v250, 0, v250, s[2:3]
	s_and_saveexec_b64 s[14:15], s[2:3]
	ds_write_b32 v202, v36
	s_or_b64 exec, exec, s[14:15]
	v_mul_f32_e32 v2, v2, v36
	ds_read_b32 v36, v1
	ds_read_b32 v37, v1 offset:4
	ds_read_b32 v38, v1 offset:8
	ds_read_b32 v39, v1 offset:12
	ds_read_b32 v40, v1 offset:32
	ds_read_b32 v41, v1 offset:36
	ds_read_b32 v42, v1 offset:40
	ds_read_b32 v43, v1 offset:44
	ds_read_b32 v44, v1 offset:64
	ds_read_b32 v45, v1 offset:68
	ds_read_b32 v46, v1 offset:72
	ds_read_b32 v47, v1 offset:76
	ds_read_b32 v48, v1 offset:96
	ds_read_b32 v49, v1 offset:100
	ds_read_b32 v50, v1 offset:104
	ds_read_b32 v51, v1 offset:108
	s_waitcnt lgkmcnt(0)
	v_pk_mul_f32 v[20:21], v[20:21], v[36:37]
	v_pk_mul_f32 v[22:23], v[22:23], v[38:39]
	v_pk_mul_f32 v[24:25], v[24:25], v[40:41]
	v_pk_mul_f32 v[26:27], v[26:27], v[42:43]
	v_pk_mul_f32 v[28:29], v[28:29], v[44:45]
	v_pk_mul_f32 v[30:31], v[30:31], v[46:47]
	v_pk_mul_f32 v[32:33], v[32:33], v[48:49]
	v_pk_mul_f32 v[34:35], v[34:35], v[50:51]
	v_pk_mul_f32 v[4:5], v[4:5], v[36:37]
	v_pk_mul_f32 v[6:7], v[6:7], v[38:39]
	v_pk_mul_f32 v[8:9], v[8:9], v[40:41]
	v_pk_mul_f32 v[10:11], v[10:11], v[42:43]
	v_pk_mul_f32 v[12:13], v[12:13], v[44:45]
	v_pk_mul_f32 v[14:15], v[14:15], v[46:47]
	v_pk_mul_f32 v[16:17], v[16:17], v[48:49]
	v_pk_mul_f32 v[18:19], v[18:19], v[50:51]
	v_sub_f32_e32 v68, v68, v186
	v_sub_f32_e32 v69, v69, v186
	v_sub_f32_e32 v70, v70, v186
	v_sub_f32_e32 v71, v71, v186
	v_sub_f32_e32 v72, v72, v186
	v_sub_f32_e32 v73, v73, v186
	v_sub_f32_e32 v74, v74, v186
	v_sub_f32_e32 v75, v75, v186
	v_sub_f32_e32 v76, v76, v186
	v_sub_f32_e32 v77, v77, v186
	v_sub_f32_e32 v78, v78, v186
	v_sub_f32_e32 v79, v79, v186
	v_sub_f32_e32 v80, v80, v186
	v_sub_f32_e32 v81, v81, v186
	v_sub_f32_e32 v82, v82, v186
	v_sub_f32_e32 v83, v83, v186
	v_sub_f32_e32 v84, v84, v186
	v_sub_f32_e32 v85, v85, v186
	v_sub_f32_e32 v86, v86, v186
	v_sub_f32_e32 v87, v87, v186
	v_sub_f32_e32 v88, v88, v186
	v_sub_f32_e32 v89, v89, v186
	v_sub_f32_e32 v90, v90, v186
	v_sub_f32_e32 v91, v91, v186
	v_sub_f32_e32 v92, v92, v186
	v_sub_f32_e32 v93, v93, v186
	v_sub_f32_e32 v94, v94, v186
	v_sub_f32_e32 v95, v95, v186
	v_sub_f32_e32 v96, v96, v186
	v_sub_f32_e32 v97, v97, v186
	v_sub_f32_e32 v98, v98, v186
	v_sub_f32_e32 v99, v99, v186
	s_mov_b32 s56, 0x41000000
	s_branch .LBB0_1009

; __device__ __forceinline__ void ph_attn(Frame& F) {
;     ...
;         for (int t = 0; t < NT; t += 2) {
;             AT_STEP(pA0, pA1, pB0, pB1, t);
;             AT_STEP(pB0, pB1, pA0, pA1, t + 1);
;         }
.LBB0_1009:
	v_mfma_f32_32x32x16_bf16 v[36:51], v[246:249], v[250:253], 0
	v_mfma_f32_32x32x16_bf16 v[36:51], v[136:139], v[100:103], v[36:51]
	v_add_u32_e32 v52, s43, v200
	ds_read_b128 v[212:215], v181 offset:96
	ds_read_b128 v[216:219], v181 offset:128
	ds_read_b128 v[220:223], v181 offset:6752
	ds_read_b128 v[224:227], v181 offset:160
	ds_read_b128 v[228:231], v181 offset:6784
	ds_read_b128 v[238:241], v181 offset:6816
	ds_read_b128 v[160:163], v52 offset:53248
	ds_read_b128 v[164:167], v52 offset:53280
	ds_read_b128 v[184:187], v52 offset:57856
	ds_read_b128 v[180:183], v52 offset:57888
	ds_read_b128 v[156:159], v52 offset:53312
	ds_read_b128 v[152:155], v52 offset:53344
	v_add_u32_e32 v209, s41, v189
	v_mfma_f32_32x32x16_bf16 v[36:51], v[148:151], v[104:107], v[36:51]
	ds_read_b128 v[176:179], v52 offset:57920
	ds_read_b128 v[148:151], v52 offset:57952
	v_exp_f32_e32 v211, v84
	v_exp_f32_e32 v232, v68
	v_exp_f32_e32 v233, v85
	v_mfma_f32_32x32x16_bf16 v[52:67], v[246:249], v[250:253], 0
	v_mfma_f32_32x32x16_bf16 v[52:67], v[144:147], v[100:103], v[52:67]
	v_exp_f32_e32 v235, v69
	v_add_f32_e32 v68, v211, v232
	v_add_f32_e32 v69, v233, v235
	v_add_f32_e32 v68, v69, v68
	v_mfma_f32_32x32x16_bf16 v[52:67], v[172:175], v[104:107], v[52:67]
	v_exp_f32_e32 v173, v70
	v_exp_f32_e32 v172, v86
	v_exp_f32_e32 v174, v87
	v_exp_f32_e32 v175, v71
	v_add_f32_e32 v69, v172, v173
	v_add_f32_e32 v68, v69, v68
	v_mfma_f32_32x32x16_bf16 v[52:67], v[168:171], v[108:111], v[52:67]
	v_add_f32_e32 v69, v174, v175
	v_add_f32_e32 v168, v69, v68
	v_exp_f32_e32 v71, v88
	v_exp_f32_e32 v85, v72
	v_exp_f32_e32 v70, v89
	v_exp_f32_e32 v84, v73
	v_exp_f32_e32 v73, v90
	v_exp_f32_e32 v87, v74
	v_exp_f32_e32 v72, v91
	v_exp_f32_e32 v86, v75
	v_pk_add_f32 v[68:69], v[70:71], v[84:85]
	v_mfma_f32_32x32x16_bf16 v[36:51], v[140:143], v[108:111], v[36:51]
	v_add_f32_e32 v69, v69, v168
	v_add_f32_e32 v74, v68, v69
	v_add_f32_e64 v68, v72, v86
	v_add_f32_e64 v69, v73, v87
	ds_read_b128 v[132:135], v209
	ds_read_b128 v[128:131], v209 offset:32
	ds_read_b128 v[136:139], v209 offset:6656
	ds_read_b128 v[124:127], v209 offset:64
	v_add_f32_e32 v69, v69, v74
	v_add_f32_e32 v168, v68, v69
	v_exp_f32_e32 v75, v92
	v_exp_f32_e32 v89, v76
	v_exp_f32_e32 v74, v93
	v_exp_f32_e32 v88, v77
	v_exp_f32_e32 v77, v94
	s_waitcnt lgkmcnt(12)
	v_mfma_f32_32x32x16_bf16 v[36:51], v[220:223], v[112:115], v[36:51]
	v_exp_f32_e32 v91, v78
	v_exp_f32_e32 v76, v95
	v_exp_f32_e32 v90, v79
	v_pk_add_f32 v[68:69], v[74:75], v[88:89]
	ds_read_b128 v[144:147], v209 offset:6688
	ds_read_b128 v[140:143], v209 offset:6720
	v_mfma_f32_32x32x16_bf16 v[52:67], v[212:215], v[112:115], v[52:67]
	v_add_f32_e32 v69, v69, v168
	v_add_f32_e32 v78, v68, v69
	v_add_f32_e64 v68, v76, v90
	v_add_f32_e64 v69, v77, v91
	v_add_f32_e32 v69, v69, v78
	v_add_f32_e32 v168, v68, v69
	v_mfma_f32_32x32x16_bf16 v[36:51], v[228:231], v[116:119], v[36:51]
	v_exp_f32_e32 v79, v96
	v_exp_f32_e32 v93, v80
	v_exp_f32_e32 v78, v97
	v_exp_f32_e32 v92, v81
	v_mfma_f32_32x32x16_bf16 v[52:67], v[216:219], v[116:119], v[52:67]
	v_exp_f32_e32 v95, v98
	v_exp_f32_e32 v97, v82
	v_exp_f32_e32 v94, v99
	v_mfma_f32_32x32x16_bf16 v[36:51], v[238:241], v[120:123], v[36:51]
	v_exp_f32_e32 v96, v83
	v_pk_add_f32 v[68:69], v[78:79], v[92:93]
	s_nop 0
	v_add_f32_e32 v69, v69, v168
	v_add_f32_e32 v80, v68, v69
	v_pk_add_f32 v[68:69], v[94:95], v[96:97]
	v_mfma_f32_32x32x16_bf16 v[52:67], v[224:227], v[120:123], v[52:67]
	v_add_f32_e32 v69, v69, v80
	v_add_f32_e32 v68, v68, v69
	v_add_f32_e32 v209, v2, v68
	v_cvt_pk_bf16_f32 v68, v211, v233
	v_cvt_pk_bf16_f32 v69, v172, v174
	v_cvt_pk_bf16_f32 v70, v71, v70
	v_cvt_pk_bf16_f32 v71, v73, v72
	v_cvt_pk_bf16_f32 v80, v75, v74
	v_cvt_pk_bf16_f32 v81, v77, v76
	s_waitcnt lgkmcnt(0)
	v_mfma_f32_32x32x16_bf16 v[4:19], v[68:71], v[184:187], v[4:19]
	v_cvt_pk_bf16_f32 v82, v79, v78
	v_cvt_pk_bf16_f32 v83, v95, v94
	v_cvt_pk_bf16_f32 v76, v232, v235
	v_cvt_pk_bf16_f32 v77, v173, v175
	v_mfma_f32_32x32x16_bf16 v[20:35], v[68:71], v[160:163], v[20:35]
	v_cvt_pk_bf16_f32 v78, v85, v84
	v_cvt_pk_bf16_f32 v79, v87, v86
	v_cvt_pk_bf16_f32 v72, v89, v88
	v_cvt_pk_bf16_f32 v73, v91, v90
	v_mfma_f32_32x32x16_bf16 v[4:19], v[80:83], v[180:183], v[4:19]
	v_cvt_pk_bf16_f32 v74, v93, v92
	v_cvt_pk_bf16_f32 v75, v97, v96
	s_cmp_ge_u32 s42, s36
	s_cbranch_scc1 .Lattn_exit
	s_mov_b32 s14, s41
	s_mov_b32 s15, s38
	s_mov_b32 s41, s45
	s_mov_b32 s38, s44
	s_mov_b32 s44, s40
	s_mov_b32 s40, s43
	s_mov_b32 s46, s42
	s_add_i32 s42, s46, 4
	s_min_u32 s43, s42, s37
	s_add_i32 s42, s46, 2
	s_min_u32 s45, s42, s37
	s_mulk_i32 s43, 0x3000
	s_add_u32 s48, s10, s43
	s_addc_u32 s49, s11, 0
	s_lshl_b32 s43, s45, 13
	s_add_u32 s50, s12, s43
	s_addc_u32 s51, s13, 0
	s_add_i32 m0, s22, s38
	s_and_b64 s[52:53], s[4:5], exec
	s_waitcnt vmcnt(3) lgkmcnt(0)
	s_barrier
	s_branch .LBB0_999

; __device__ __forceinline__ void ph_attn(Frame& F) {
;     ...
;         AT_PVMM(vf);
;         if (AT_PRIO) __builtin_amdgcn_s_setprio(0);
;     ...
;         l_run += __shfl_xor(l_run, 32);
;         if (hi == 0) wsf[r32] = 1.0f / l_run;
.LBB0_1011:
	v_mfma_f32_32x32x16_bf16 v[20:35], v[80:83], v[164:167], v[20:35]
	v_mfma_f32_32x32x16_bf16 v[20:35], v[76:79], v[156:159], v[20:35]
	v_mfma_f32_32x32x16_bf16 v[4:19], v[76:79], v[176:179], v[4:19]
	v_mfma_f32_32x32x16_bf16 v[20:35], v[72:75], v[152:155], v[20:35]
	v_mfma_f32_32x32x16_bf16 v[4:19], v[72:75], v[148:151], v[4:19]
	s_setprio 0
	v_and_b32_e32 v36, 64, v208
	v_xor_b32_e32 v2, 32, v208
	v_add_u32_e32 v36, 64, v36
	v_cmp_lt_i32_e32 vcc, v2, v36
	s_nop 1
	v_cndmask_b32_e32 v2, v208, v2, vcc
	v_lshlrev_b32_e32 v2, 2, v2
	ds_bpermute_b32 v2, v2, v209
	s_and_saveexec_b64 s[10:11], s[2:3]
	s_cbranch_execz .LBB0_984
	s_waitcnt lgkmcnt(0)
	v_add_f32_e32 v2, v209, v2
	v_div_scale_f32 v36, s[12:13], v2, v2, 1.0
	v_rcp_f32_e32 v37, v36
	v_div_scale_f32 v38, vcc, 1.0, v2, 1.0
	v_fma_f32 v39, -v36, v37, 1.0
	v_fmac_f32_e32 v37, v39, v37
	v_mul_f32_e32 v39, v38, v37
	v_fma_f32 v40, -v36, v39, v38
	v_fmac_f32_e32 v39, v40, v37
	v_fma_f32 v36, -v36, v39, v38
	v_div_fmas_f32 v36, v36, v37, v39
	v_div_fixup_f32 v2, v36, v2, 1.0
	ds_write_b32 v202, v2
	s_branch .LBB0_984
